# write-through last-unit GEMM stores + DFT stores + peeled zero-C first iteration, grid barrier unchanged (no early acquire)
# speedup vs baseline: 1.0020x; 1.0020x over previous
.LBB0_503:
	v_mov_b32_e32 v58, v35
	v_mov_b32_e32 v42, v23
	v_mov_b32_e32 v30, v63
	s_waitcnt vmcnt(0)
	v_pk_mul_f32 v[6:7], v[8:9], v[58:59]
	v_mov_b32_e32 v18, v47
	v_pk_mul_f32 v[14:15], v[8:9], v[42:43]
	v_pk_fma_f32 v[6:7], v[8:9], v[30:31], v[6:7] op_sel:[1,0,0] op_sel_hi:[0,1,1]
	v_mov_b32_e32 v10, v9
	v_mov_b32_e32 v30, v35
	v_pk_fma_f32 v[14:15], v[8:9], v[18:19], v[14:15] op_sel:[1,0,0] op_sel_hi:[0,1,1]
	v_mov_b32_e32 v18, v23
	v_mov_b32_e32 v58, v63
	v_pk_mul_f32 v[12:13], v[10:11], v[30:31] op_sel_hi:[0,1]
	v_mov_b32_e32 v42, v47
	v_pk_mul_f32 v[10:11], v[10:11], v[18:19] op_sel_hi:[0,1]
	v_pk_fma_f32 v[12:13], v[8:9], v[58:59], v[12:13] op_sel_hi:[0,1,1] neg_lo:[0,0,1] neg_hi:[0,0,1]
	v_pk_fma_f32 v[8:9], v[8:9], v[42:43], v[10:11] op_sel_hi:[0,1,1] neg_lo:[0,0,1] neg_hi:[0,0,1]
	v_add_u32_e32 v10, 0x42, v156
	v_ashrrev_i32_e32 v11, 31, v10
	v_lshlrev_b64 v[10:11], s12, v[10:11]
	v_or_b32_e32 v10, s48, v10
	v_lshlrev_b64 v[10:11], 10, v[10:11]
	v_cvt_pk_bf16_f32 v6, v6, v7
	v_cvt_pk_bf16_f32 v7, v14, v15
	v_lshl_add_u64 v[10:11], v[74:75], 0, v[10:11]
	global_store_dwordx2 v[10:11], v[6:7], off sc1
	v_cvt_pk_bf16_f32 v7, v8, v9
	v_add_u32_e32 v8, 0x43, v156
	v_ashrrev_i32_e32 v9, 31, v8
	v_lshlrev_b64 v[8:9], s12, v[8:9]
	v_lshl_add_u64 v[8:9], v[8:9], 0, s[48:49]
	v_lshlrev_b64 v[8:9], 10, v[8:9]
	v_cvt_pk_bf16_f32 v6, v12, v13
	v_lshl_add_u64 v[8:9], v[74:75], 0, v[8:9]
	global_store_dwordx2 v[8:9], v[6:7], off sc1
	v_mov_b32_e32 v8, v36
	v_mov_b32_e32 v9, v60
	v_mov_b32_e32 v6, v64
	v_mov_b32_e32 v7, v32
	v_pk_mul_f32 v[8:9], v[2:3], v[8:9]
	v_mov_b32_e32 v10, v3
	v_mov_b32_e32 v12, v36
	v_mov_b32_e32 v13, v32
	v_pk_fma_f32 v[6:7], v[2:3], v[6:7], v[8:9] op_sel:[1,0,0] op_sel_hi:[0,1,1]
	v_mov_b32_e32 v8, v64
	v_mov_b32_e32 v9, v60
	v_pk_mul_f32 v[12:13], v[10:11], v[12:13] op_sel_hi:[0,1]
	v_mov_b32_e32 v14, v24
	v_mov_b32_e32 v15, v44
	v_pk_fma_f32 v[8:9], v[2:3], v[8:9], v[12:13] op_sel_hi:[0,1,1] neg_lo:[0,0,1] neg_hi:[0,0,1]
	v_mov_b32_e32 v12, v48
	v_mov_b32_e32 v13, v20
	v_pk_mul_f32 v[14:15], v[2:3], v[14:15]
	v_mov_b32_e32 v16, v24
	v_mov_b32_e32 v17, v20
	v_pk_fma_f32 v[12:13], v[2:3], v[12:13], v[14:15] op_sel:[1,0,0] op_sel_hi:[0,1,1]
	v_mov_b32_e32 v14, v48
	v_mov_b32_e32 v15, v44
	v_pk_mul_f32 v[10:11], v[10:11], v[16:17] op_sel_hi:[0,1]
	v_pk_fma_f32 v[2:3], v[2:3], v[14:15], v[10:11] op_sel_hi:[0,1,1] neg_lo:[0,0,1] neg_hi:[0,0,1]
	v_add_u32_e32 v10, 0x44, v156
	v_ashrrev_i32_e32 v11, 31, v10
	v_lshlrev_b64 v[10:11], s12, v[10:11]
	v_or_b32_e32 v10, s48, v10
	v_lshlrev_b64 v[10:11], 10, v[10:11]
	v_cvt_pk_bf16_f32 v6, v6, v7
	v_cvt_pk_bf16_f32 v7, v12, v13
	v_lshl_add_u64 v[10:11], v[74:75], 0, v[10:11]
	global_store_dwordx2 v[10:11], v[6:7], off sc1
	v_cvt_pk_bf16_f32 v7, v2, v3
	v_add_u32_e32 v2, 0x45, v156
	v_ashrrev_i32_e32 v3, 31, v2
	v_lshlrev_b64 v[2:3], s12, v[2:3]
	v_lshl_add_u64 v[2:3], v[2:3], 0, s[48:49]
	v_lshlrev_b64 v[2:3], 10, v[2:3]
	v_cvt_pk_bf16_f32 v6, v8, v9
	v_lshl_add_u64 v[2:3], v[74:75], 0, v[2:3]
	v_mov_b32_e32 v60, v37
	v_mov_b32_e32 v44, v25
	global_store_dwordx2 v[2:3], v[6:7], off sc1
	v_mov_b32_e32 v32, v65
	v_pk_mul_f32 v[2:3], v[4:5], v[60:61]
	v_mov_b32_e32 v20, v49
	v_pk_mul_f32 v[10:11], v[4:5], v[44:45]
	v_pk_fma_f32 v[2:3], v[4:5], v[32:33], v[2:3] op_sel:[1,0,0] op_sel_hi:[0,1,1]
	v_mov_b32_e32 v6, v5
	v_mov_b32_e32 v32, v37
	v_pk_fma_f32 v[10:11], v[4:5], v[20:21], v[10:11] op_sel:[1,0,0] op_sel_hi:[0,1,1]
	v_mov_b32_e32 v20, v25
	v_mov_b32_e32 v60, v65
	v_pk_mul_f32 v[8:9], v[6:7], v[32:33] op_sel_hi:[0,1]
	v_mov_b32_e32 v44, v49
	v_pk_mul_f32 v[6:7], v[6:7], v[20:21] op_sel_hi:[0,1]
	v_pk_fma_f32 v[8:9], v[4:5], v[60:61], v[8:9] op_sel_hi:[0,1,1] neg_lo:[0,0,1] neg_hi:[0,0,1]
	v_pk_fma_f32 v[4:5], v[4:5], v[44:45], v[6:7] op_sel_hi:[0,1,1] neg_lo:[0,0,1] neg_hi:[0,0,1]
	v_add_u32_e32 v6, 0x46, v156
	v_ashrrev_i32_e32 v7, 31, v6
	v_lshlrev_b64 v[6:7], s12, v[6:7]
	v_or_b32_e32 v6, s48, v6
	v_lshlrev_b64 v[6:7], 10, v[6:7]
	v_cvt_pk_bf16_f32 v2, v2, v3
	v_cvt_pk_bf16_f32 v3, v10, v11
	v_lshl_add_u64 v[6:7], v[74:75], 0, v[6:7]
	global_store_dwordx2 v[6:7], v[2:3], off sc1
	v_cvt_pk_bf16_f32 v3, v4, v5
	v_add_u32_e32 v4, 0x47, v156
	v_ashrrev_i32_e32 v5, 31, v4
	v_lshlrev_b64 v[4:5], s12, v[4:5]
	v_lshl_add_u64 v[4:5], v[4:5], 0, s[48:49]
	v_lshlrev_b64 v[4:5], 10, v[4:5]
	v_cvt_pk_bf16_f32 v2, v8, v9
	v_lshl_add_u64 v[4:5], v[74:75], 0, v[4:5]
	global_store_dwordx2 v[4:5], v[2:3], off sc1
	s_branch .LBB0_487
